# attention: window-masked chunks use the pipelined kt loop too; mask compare/select only on tiles the window cuts, via SGPR-pair masks
# speedup vs baseline: 1.0114x; 1.0067x over previous
; __device__ __forceinline__ void attn_mfma(PP p, unsigned char* shm, int wv) {
;     ...
;             const int kt_lo = (ci == 0 && qh == 1) ? 2 : 0, kt_hi = (ci == 2 && qh == 0) ? 2 : 4;
; #pragma unroll 1
;             for (int kt = kt_lo; kt < kt_hi; ++kt) {
;                 bf16x8 kf[4];
; #pragma unroll
;                 for (int st = 0; st < 4; ++st) kf[st] = *(const bf16x8*)(Ks + (32 * kt + l31) * 72 + 16 * st + 8 * hl);
;                 bf16x8 vf[2][2];
; #pragma unroll
;                 for (int db = 0; db < 2; ++db)
; #pragma unroll
;                     for (int s2 = 0; s2 < 2; ++s2) {
;                         const bf16_t* vp = Vt + (32 * db + l31) * 132 + 32 * kt + 16 * s2 + 4 * hl;
;                         const u32x2 lo = *(const u32x2*)vp, hi = *(const u32x2*)(vp + 8);
;                         u32x4 w; w.x = lo.x; w.y = lo.y; w.z = hi.x; w.w = hi.y;
;                         vf[db][s2] = __builtin_bit_cast(bf16x8, w);
;                     }
; #pragma unroll
;                 for (int qi = 0; qi < 2; ++qi) {
;                     f32x16 s;
; #pragma unroll
;                     for (int i = 0; i < 16; ++i) s[i] = 0.f;
;                     __builtin_amdgcn_s_setprio(1);
; #pragma unroll
;                     for (int st = 0; st < 4; ++st) s = __builtin_amdgcn_mfma_f32_32x32x16_bf16(kf[st], qf[qi][st], s, 0, 0, 0);
;                     __builtin_amdgcn_s_setprio(0);
;                     if (ci == 0 || ci == 2) {
;                         asm volatile("");
;                         const int dl = (ci == 0) ? (32 * kt + 4 * hl - (64 * qh + 32 * qi + l31)) : ((64 * qh + 32 * qi + l31) - 32 * kt - 4 * hl);
; #pragma unroll
;                         for (int i = 0; i < 16; ++i) {
;                             const int ki = 8 * (i >> 2) + (i & 3);
;                             const bool ok = (ci == 0) ? (dl + ki >= 0) : (dl - ki >= 0);
;                             s[i] = ok ? s[i] : -1e30f;
;                         }
;                     }
;                     float mx = s[0];
; #pragma unroll
;                     for (int i = 1; i < 16; ++i) mx = fmaxf(mx, s[i]);
;                     mx = fmaxf(mx, __shfl_xor(mx, 32));
;                     const float mnew = fmaxf(mrun[qi], mx * SC2);
;                     if (__builtin_amdgcn_ballot_w64(mnew > mrun[qi]) != 0ull) {
.Lattn_p_entry_m0:
	s_bfe_u32 s28, s56, 0x10006
	s_lshl_b32 s28, s28, 1
	ds_read_b128 v[158:161], v200
	ds_read_b128 v[154:157], v200 offset:32
	ds_read_b128 v[150:153], v200 offset:64
	ds_read_b128 v[146:149], v200 offset:96
	v_add_u32_e32 v200, 0x1200, v200
	s_add_i32 s20, s41, -1
	s_waitcnt vmcnt(4) lgkmcnt(3)
	v_mfma_f32_32x32x16_bf16 v[66:81], v[158:161], v[82:85], 0
	s_waitcnt lgkmcnt(2)
	v_mfma_f32_32x32x16_bf16 v[66:81], v[154:157], v[86:89], v[66:81]
	s_waitcnt lgkmcnt(1)
	v_mfma_f32_32x32x16_bf16 v[66:81], v[150:153], v[90:93], v[66:81]
	s_waitcnt lgkmcnt(0)
	v_mfma_f32_32x32x16_bf16 v[66:81], v[146:149], v[94:97], v[66:81]
	s_nop 4
	s_cmp_ge_u32 s40, s20
	s_cbranch_scc1 .Lattn_p_last_m0
.Lattn_p_loop_m0:
	v_add_u32_e32 v236, 0x2000, v199
	ds_read2_b64 v[142:145], v199 offset1:2
	ds_read2_b64 v[138:141], v199 offset0:4 offset1:6
	ds_read2_b64 v[134:137], v236 offset0:32 offset1:34
	ds_read2_b64 v[130:133], v236 offset0:36 offset1:38
	v_add_u32_e32 v199, 64, v199
	v_lshl_add_u32 v252, s40, 5, v189
	v_add_u32_e32 v253, -16, v252
	v_add_u32_e32 v252, 16, v252
	s_sub_i32 s29, s40, s28
	v_mfma_f32_32x32x16_bf16 v[220:235], v[158:161], v[98:101], 0
	s_cmp_gt_i32 s29, 0
	s_cbranch_scc1 .Lattn_p_mk0_am0
	v_cmp_lt_i32_e64 s[42:43], 15, v252
	v_cmp_lt_i32_e64 s[44:45], 14, v252
	v_cmp_lt_i32_e64 s[46:47], 13, v252
	v_cmp_lt_i32_e64 s[48:49], 12, v252
	v_cndmask_b32_e64 v66, v194, v66, s[42:43]
	v_cndmask_b32_e64 v67, v194, v67, s[44:45]
	v_cndmask_b32_e64 v68, v194, v68, s[46:47]
	v_cndmask_b32_e64 v69, v194, v69, s[48:49]
	v_cmp_lt_i32_e64 s[42:43], 7, v252
	v_cmp_lt_i32_e64 s[44:45], 6, v252
	v_cmp_lt_i32_e64 s[46:47], 5, v252
	v_cmp_lt_i32_e64 s[48:49], 4, v252
	v_cndmask_b32_e64 v70, v194, v70, s[42:43]
	v_cndmask_b32_e64 v71, v194, v71, s[44:45]
	v_cndmask_b32_e64 v72, v194, v72, s[46:47]
	v_cndmask_b32_e64 v73, v194, v73, s[48:49]
	v_cmp_lt_i32_e64 s[42:43], -1, v252
	v_cmp_lt_i32_e64 s[44:45], -2, v252
	v_cmp_lt_i32_e64 s[46:47], -3, v252
	v_cmp_lt_i32_e64 s[48:49], -4, v252
	v_cndmask_b32_e64 v74, v194, v74, s[42:43]
	v_cndmask_b32_e64 v75, v194, v75, s[44:45]
	v_cndmask_b32_e64 v76, v194, v76, s[46:47]
	v_cndmask_b32_e64 v77, v194, v77, s[48:49]
	v_cmp_lt_i32_e64 s[42:43], -9, v252
	v_cmp_lt_i32_e64 s[44:45], -10, v252
	v_cmp_lt_i32_e64 s[46:47], -11, v252
	v_cmp_lt_i32_e64 s[48:49], -12, v252
	v_cndmask_b32_e64 v78, v194, v78, s[42:43]
	v_cndmask_b32_e64 v79, v194, v79, s[44:45]
	v_cndmask_b32_e64 v80, v194, v80, s[46:47]
	v_cndmask_b32_e64 v81, v194, v81, s[48:49]
.Lattn_p_mk0_am0:
	v_max3_f32 v244, v66, v67, v68
	v_max3_f32 v245, v69, v70, v71
	v_max3_f32 v244, v244, v72, v73
	v_max3_f32 v245, v245, v74, v75
	v_max3_f32 v244, v244, v76, v77
	v_max3_f32 v245, v245, v78, v79
	v_mfma_f32_32x32x16_bf16 v[220:235], v[154:157], v[102:105], v[220:235]
	v_max3_f32 v244, v244, v80, v81
	v_max_f32_e32 v244, v244, v245
	v_mov_b32_e32 v245, v244
	v_max_f32_e32 v248, v197, v197
	s_nop 0
	v_permlane32_swap_b32_e32 v244, v245
	v_max_f32_e32 v244, v244, v245
	v_mul_f32_e32 v244, 0x3e38aa3b, v244
	v_max_f32_e32 v248, v248, v244
	v_cmp_gt_f32_e32 vcc, v248, v197
	s_cbranch_vccz .Lattn_p_nr0_am0
	v_sub_f32_e32 v240, v197, v248
	v_exp_f32_e32 v240, v240
	v_mov_b32_e32 v197, v248
	v_mul_f32_e32 v196, v196, v240
	v_pk_mul_f32 v[64:65], v[64:65], v[240:241] op_sel_hi:[1,0]
	v_pk_mul_f32 v[62:63], v[62:63], v[240:241] op_sel_hi:[1,0]
	v_pk_mul_f32 v[60:61], v[60:61], v[240:241] op_sel_hi:[1,0]
	v_pk_mul_f32 v[58:59], v[58:59], v[240:241] op_sel_hi:[1,0]
	v_pk_mul_f32 v[56:57], v[56:57], v[240:241] op_sel_hi:[1,0]
	v_pk_mul_f32 v[54:55], v[54:55], v[240:241] op_sel_hi:[1,0]
	v_pk_mul_f32 v[52:53], v[52:53], v[240:241] op_sel_hi:[1,0]
	v_pk_mul_f32 v[50:51], v[50:51], v[240:241] op_sel_hi:[1,0]
	v_pk_mul_f32 v[48:49], v[48:49], v[240:241] op_sel_hi:[1,0]
	v_pk_mul_f32 v[46:47], v[46:47], v[240:241] op_sel_hi:[1,0]
	v_pk_mul_f32 v[44:45], v[44:45], v[240:241] op_sel_hi:[1,0]
	v_pk_mul_f32 v[42:43], v[42:43], v[240:241] op_sel_hi:[1,0]
	v_pk_mul_f32 v[40:41], v[40:41], v[240:241] op_sel_hi:[1,0]
	v_pk_mul_f32 v[38:39], v[38:39], v[240:241] op_sel_hi:[1,0]
	v_pk_mul_f32 v[36:37], v[36:37], v[240:241] op_sel_hi:[1,0]
	v_pk_mul_f32 v[34:35], v[34:35], v[240:241] op_sel_hi:[1,0]
; __device__ __forceinline__ void attn_mfma(PP p, unsigned char* shm, int wv) {
;     ...
;                     if (ci == 0 || ci == 2) {
;                         asm volatile("");
;                         const int dl = (ci == 0) ? (32 * kt + 4 * hl - (64 * qh + 32 * qi + l31)) : ((64 * qh + 32 * qi + l31) - 32 * kt - 4 * hl);
; #pragma unroll
;                         for (int i = 0; i < 16; ++i) {
;                             const int ki = 8 * (i >> 2) + (i & 3);
;                             const bool ok = (ci == 0) ? (dl + ki >= 0) : (dl - ki >= 0);
;                             s[i] = ok ? s[i] : -1e30f;
;                         }
;                     }
;                     float mx = s[0];
; #pragma unroll
;                     for (int i = 1; i < 16; ++i) mx = fmaxf(mx, s[i]);
;                     mx = fmaxf(mx, __shfl_xor(mx, 32));
;                     const float mnew = fmaxf(mrun[qi], mx * SC2);
;                     if (__builtin_amdgcn_ballot_w64(mnew > mrun[qi]) != 0ull) {
;                         const float alpha = __builtin_amdgcn_exp2f(mrun[qi] - mnew);
;                         lrun[qi] *= alpha;
; #pragma unroll
;                         for (int db = 0; db < 2; ++db)
; #pragma unroll
;                             for (int i = 0; i < 16; ++i) oacc[db][qi][i] *= alpha;
;                         mrun[qi] = mnew;
;                     }
;                     float ls = 0.f;
; #pragma unroll
;                     for (int i = 0; i < 16; ++i) { s[i] = __builtin_amdgcn_exp2f(__builtin_fmaf(s[i], SC2, -mnew)); ls += s[i]; }
;                     lrun[qi] += ls;
;                     bf16x8 pf[2];
; #pragma unroll
;                     for (int s2 = 0; s2 < 2; ++s2) {
;                         u32x4 w; w.x = cvt_pk_bf16(s[8 * s2 + 0], s[8 * s2 + 1]); w.y = cvt_pk_bf16(s[8 * s2 + 2], s[8 * s2 + 3]);
;                         w.z = cvt_pk_bf16(s[8 * s2 + 4], s[8 * s2 + 5]); w.w = cvt_pk_bf16(s[8 * s2 + 6], s[8 * s2 + 7]);
;                         pf[s2] = __builtin_bit_cast(bf16x8, w);
;                     }
; #pragma unroll
;                     for (int db = 0; db < 2; ++db)
; #pragma unroll
;                         for (int s2 = 0; s2 < 2; ++s2) oacc[db][qi] = __builtin_amdgcn_mfma_f32_32x32x16_bf16(vf[db][s2], pf[s2], oacc[db][qi], 0, 0, 0);
;                 }
.Lattn_p_nr0_am0:
	v_fma_f32 v236, v66, s31, -v248
	v_fma_f32 v237, v67, s31, -v248
	v_fma_f32 v238, v68, s31, -v248
	v_fma_f32 v239, v69, s31, -v248
	v_exp_f32_e32 v66, v236
	v_exp_f32_e32 v67, v237
	v_exp_f32_e32 v68, v238
	v_exp_f32_e32 v69, v239
	v_mfma_f32_32x32x16_bf16 v[220:235], v[150:153], v[106:109], v[220:235]
	v_fma_f32 v236, v70, s31, -v248
	v_fma_f32 v237, v71, s31, -v248
	v_fma_f32 v238, v72, s31, -v248
	v_fma_f32 v239, v73, s31, -v248
	v_exp_f32_e32 v70, v236
	v_exp_f32_e32 v71, v237
	v_exp_f32_e32 v72, v238
	v_exp_f32_e32 v73, v239
	v_fma_f32 v236, v74, s31, -v248
	v_fma_f32 v237, v75, s31, -v248
	v_fma_f32 v238, v76, s31, -v248
	v_fma_f32 v239, v77, s31, -v248
	v_exp_f32_e32 v74, v236
	v_exp_f32_e32 v75, v237
	v_exp_f32_e32 v76, v238
	v_exp_f32_e32 v77, v239
	v_mfma_f32_32x32x16_bf16 v[220:235], v[146:149], v[110:113], v[220:235]
	ds_read_b128 v[158:161], v200
	ds_read_b128 v[154:157], v200 offset:32
	ds_read_b128 v[150:153], v200 offset:64
	ds_read_b128 v[146:149], v200 offset:96
	v_add_u32_e32 v200, 0x1200, v200
	v_fma_f32 v236, v78, s31, -v248
	v_fma_f32 v237, v79, s31, -v248
	v_fma_f32 v238, v80, s31, -v248
	v_fma_f32 v239, v81, s31, -v248
	v_exp_f32_e32 v78, v236
	v_exp_f32_e32 v79, v237
	v_exp_f32_e32 v80, v238
	v_exp_f32_e32 v81, v239
	v_cvt_pk_bf16_f32 v204, v66, v67
	v_cvt_pk_bf16_f32 v205, v68, v69
	v_cvt_pk_bf16_f32 v206, v70, v71
	v_cvt_pk_bf16_f32 v207, v72, v73
	v_cvt_pk_bf16_f32 v208, v74, v75
	v_cvt_pk_bf16_f32 v209, v76, v77
	v_cvt_pk_bf16_f32 v210, v78, v79
	v_cvt_pk_bf16_f32 v211, v80, v81
	s_waitcnt lgkmcnt(4)
	v_mfma_f32_32x32x16_bf16 v[50:65], v[142:145], v[204:207], v[50:65]
	v_add_f32_e32 v250, 0, v66
	v_add_f32_e32 v250, v67, v250
	v_add_f32_e32 v250, v68, v250
	v_add_f32_e32 v250, v69, v250
	v_add_f32_e32 v250, v70, v250
	v_add_f32_e32 v250, v71, v250
	v_add_f32_e32 v250, v72, v250
	v_add_f32_e32 v250, v73, v250
	v_mfma_f32_32x32x16_bf16 v[34:49], v[134:137], v[204:207], v[34:49]
	v_add_f32_e32 v250, v74, v250
	v_add_f32_e32 v250, v75, v250
	v_add_f32_e32 v250, v76, v250
	v_add_f32_e32 v250, v77, v250
	v_add_f32_e32 v250, v78, v250
	v_add_f32_e32 v250, v79, v250
	v_add_f32_e32 v250, v80, v250
	v_add_f32_e32 v250, v81, v250
	v_add_f32_e32 v196, v250, v196
	v_mfma_f32_32x32x16_bf16 v[50:65], v[138:141], v[208:211], v[50:65]
	s_cmp_gt_i32 s29, 1
	s_cbranch_scc1 .Lattn_p_mk1_am0
	v_cmp_lt_i32_e64 s[42:43], 15, v253
	v_cmp_lt_i32_e64 s[44:45], 14, v253
	v_cmp_lt_i32_e64 s[46:47], 13, v253
	v_cmp_lt_i32_e64 s[48:49], 12, v253
	v_cndmask_b32_e64 v220, v194, v220, s[42:43]
	v_cndmask_b32_e64 v221, v194, v221, s[44:45]
	v_cndmask_b32_e64 v222, v194, v222, s[46:47]
	v_cndmask_b32_e64 v223, v194, v223, s[48:49]
	v_cmp_lt_i32_e64 s[42:43], 7, v253
	v_cmp_lt_i32_e64 s[44:45], 6, v253
	v_cmp_lt_i32_e64 s[46:47], 5, v253
	v_cmp_lt_i32_e64 s[48:49], 4, v253
	v_cndmask_b32_e64 v224, v194, v224, s[42:43]
	v_cndmask_b32_e64 v225, v194, v225, s[44:45]
	v_cndmask_b32_e64 v226, v194, v226, s[46:47]
	v_cndmask_b32_e64 v227, v194, v227, s[48:49]
	v_cmp_lt_i32_e64 s[42:43], -1, v253
	v_cmp_lt_i32_e64 s[44:45], -2, v253
	v_cmp_lt_i32_e64 s[46:47], -3, v253
	v_cmp_lt_i32_e64 s[48:49], -4, v253
	v_cndmask_b32_e64 v228, v194, v228, s[42:43]
	v_cndmask_b32_e64 v229, v194, v229, s[44:45]
	v_cndmask_b32_e64 v230, v194, v230, s[46:47]
	v_cndmask_b32_e64 v231, v194, v231, s[48:49]
	v_cmp_lt_i32_e64 s[42:43], -9, v253
	v_cmp_lt_i32_e64 s[44:45], -10, v253
	v_cmp_lt_i32_e64 s[46:47], -11, v253
	v_cmp_lt_i32_e64 s[48:49], -12, v253
	v_cndmask_b32_e64 v232, v194, v232, s[42:43]
	v_cndmask_b32_e64 v233, v194, v233, s[44:45]
	v_cndmask_b32_e64 v234, v194, v234, s[46:47]
	v_cndmask_b32_e64 v235, v194, v235, s[48:49]
.Lattn_p_mk1_am0:
	v_max3_f32 v246, v220, v221, v222
	v_max3_f32 v247, v223, v224, v225
	v_max3_f32 v246, v246, v226, v227
	v_max3_f32 v247, v247, v228, v229
	v_max3_f32 v246, v246, v230, v231
	v_max3_f32 v247, v247, v232, v233
	v_mfma_f32_32x32x16_bf16 v[34:49], v[130:133], v[208:211], v[34:49]
	v_max3_f32 v246, v246, v234, v235
	v_max_f32_e32 v246, v246, v247
	v_mov_b32_e32 v247, v246
	v_max_f32_e32 v249, v198, v198
	s_nop 0
	v_permlane32_swap_b32_e32 v246, v247
	v_max_f32_e32 v246, v246, v247
	v_mul_f32_e32 v246, 0x3e38aa3b, v246
	v_max_f32_e32 v249, v249, v246
	v_cmp_gt_f32_e32 vcc, v249, v198
	s_cbranch_vccz .Lattn_p_nr1_am0
	v_sub_f32_e32 v240, v198, v249
	v_exp_f32_e32 v240, v240
	v_mov_b32_e32 v198, v249
	v_mul_f32_e32 v1, v1, v240
	v_pk_mul_f32 v[32:33], v[32:33], v[240:241] op_sel_hi:[1,0]
	v_pk_mul_f32 v[30:31], v[30:31], v[240:241] op_sel_hi:[1,0]
	v_pk_mul_f32 v[28:29], v[28:29], v[240:241] op_sel_hi:[1,0]
	v_pk_mul_f32 v[26:27], v[26:27], v[240:241] op_sel_hi:[1,0]
	v_pk_mul_f32 v[24:25], v[24:25], v[240:241] op_sel_hi:[1,0]
	v_pk_mul_f32 v[22:23], v[22:23], v[240:241] op_sel_hi:[1,0]
	v_pk_mul_f32 v[20:21], v[20:21], v[240:241] op_sel_hi:[1,0]
	v_pk_mul_f32 v[18:19], v[18:19], v[240:241] op_sel_hi:[1,0]
	v_pk_mul_f32 v[16:17], v[16:17], v[240:241] op_sel_hi:[1,0]
	v_pk_mul_f32 v[14:15], v[14:15], v[240:241] op_sel_hi:[1,0]
	v_pk_mul_f32 v[12:13], v[12:13], v[240:241] op_sel_hi:[1,0]
	v_pk_mul_f32 v[10:11], v[10:11], v[240:241] op_sel_hi:[1,0]
	v_pk_mul_f32 v[8:9], v[8:9], v[240:241] op_sel_hi:[1,0]
	v_pk_mul_f32 v[6:7], v[6:7], v[240:241] op_sel_hi:[1,0]
	v_pk_mul_f32 v[4:5], v[4:5], v[240:241] op_sel_hi:[1,0]
	v_pk_mul_f32 v[2:3], v[2:3], v[240:241] op_sel_hi:[1,0]

; __device__ __forceinline__ void attn_mfma(PP p, unsigned char* shm, int wv) {
;     ...
;                     if (ci == 0 || ci == 2) {
;                         asm volatile("");
;                         const int dl = (ci == 0) ? (32 * kt + 4 * hl - (64 * qh + 32 * qi + l31)) : ((64 * qh + 32 * qi + l31) - 32 * kt - 4 * hl);
; #pragma unroll
;                         for (int i = 0; i < 16; ++i) {
;                             const int ki = 8 * (i >> 2) + (i & 3);
;                             const bool ok = (ci == 0) ? (dl + ki >= 0) : (dl - ki >= 0);
;                             s[i] = ok ? s[i] : -1e30f;
;                         }
;                     }
;                     float mx = s[0];
; #pragma unroll
;                     for (int i = 1; i < 16; ++i) mx = fmaxf(mx, s[i]);
;                     mx = fmaxf(mx, __shfl_xor(mx, 32));
;                     const float mnew = fmaxf(mrun[qi], mx * SC2);
;                     if (__builtin_amdgcn_ballot_w64(mnew > mrun[qi]) != 0ull) {
;                         const float alpha = __builtin_amdgcn_exp2f(mrun[qi] - mnew);
;                         lrun[qi] *= alpha;
; #pragma unroll
;                         for (int db = 0; db < 2; ++db)
; #pragma unroll
;                             for (int i = 0; i < 16; ++i) oacc[db][qi][i] *= alpha;
;                         mrun[qi] = mnew;
;                     }
;                     float ls = 0.f;
; #pragma unroll
;                     for (int i = 0; i < 16; ++i) { s[i] = __builtin_amdgcn_exp2f(__builtin_fmaf(s[i], SC2, -mnew)); ls += s[i]; }
;                     lrun[qi] += ls;
;                     bf16x8 pf[2];
; #pragma unroll
;                     for (int s2 = 0; s2 < 2; ++s2) {
;                         u32x4 w; w.x = cvt_pk_bf16(s[8 * s2 + 0], s[8 * s2 + 1]); w.y = cvt_pk_bf16(s[8 * s2 + 2], s[8 * s2 + 3]);
;                         w.z = cvt_pk_bf16(s[8 * s2 + 4], s[8 * s2 + 5]); w.w = cvt_pk_bf16(s[8 * s2 + 6], s[8 * s2 + 7]);
;                         pf[s2] = __builtin_bit_cast(bf16x8, w);
;                     }
; #pragma unroll
;                     for (int db = 0; db < 2; ++db)
; #pragma unroll
;                         for (int s2 = 0; s2 < 2; ++s2) oacc[db][qi] = __builtin_amdgcn_mfma_f32_32x32x16_bf16(vf[db][s2], pf[s2], oacc[db][qi], 0, 0, 0);
.Lattn_p_nr0_bm0:
	v_fma_f32 v236, v66, s31, -v248
	v_fma_f32 v237, v67, s31, -v248
	v_fma_f32 v238, v68, s31, -v248
	v_fma_f32 v239, v69, s31, -v248
	v_exp_f32_e32 v66, v236
	v_exp_f32_e32 v67, v237
	v_exp_f32_e32 v68, v238
	v_exp_f32_e32 v69, v239
	v_mfma_f32_32x32x16_bf16 v[220:235], v[150:153], v[106:109], v[220:235]
	v_fma_f32 v236, v70, s31, -v248
	v_fma_f32 v237, v71, s31, -v248
	v_fma_f32 v238, v72, s31, -v248
	v_fma_f32 v239, v73, s31, -v248
	v_exp_f32_e32 v70, v236
	v_exp_f32_e32 v71, v237
	v_exp_f32_e32 v72, v238
	v_exp_f32_e32 v73, v239
	v_fma_f32 v236, v74, s31, -v248
	v_fma_f32 v237, v75, s31, -v248
	v_fma_f32 v238, v76, s31, -v248
	v_fma_f32 v239, v77, s31, -v248
	v_exp_f32_e32 v74, v236
	v_exp_f32_e32 v75, v237
	v_exp_f32_e32 v76, v238
	v_exp_f32_e32 v77, v239
	v_mfma_f32_32x32x16_bf16 v[220:235], v[146:149], v[110:113], v[220:235]
	v_fma_f32 v236, v78, s31, -v248
	v_fma_f32 v237, v79, s31, -v248
	v_fma_f32 v238, v80, s31, -v248
	v_fma_f32 v239, v81, s31, -v248
	v_exp_f32_e32 v78, v236
	v_exp_f32_e32 v79, v237
	v_exp_f32_e32 v80, v238
	v_exp_f32_e32 v81, v239
	v_cvt_pk_bf16_f32 v204, v66, v67
	v_cvt_pk_bf16_f32 v205, v68, v69
	v_cvt_pk_bf16_f32 v206, v70, v71
	v_cvt_pk_bf16_f32 v207, v72, v73
	v_cvt_pk_bf16_f32 v208, v74, v75
	v_cvt_pk_bf16_f32 v209, v76, v77
	v_cvt_pk_bf16_f32 v210, v78, v79
	v_cvt_pk_bf16_f32 v211, v80, v81
	s_waitcnt lgkmcnt(0)
	v_mfma_f32_32x32x16_bf16 v[50:65], v[142:145], v[204:207], v[50:65]
	v_add_f32_e32 v250, 0, v66
	v_add_f32_e32 v250, v67, v250
	v_add_f32_e32 v250, v68, v250
	v_add_f32_e32 v250, v69, v250
	v_add_f32_e32 v250, v70, v250
	v_add_f32_e32 v250, v71, v250
	v_add_f32_e32 v250, v72, v250
	v_add_f32_e32 v250, v73, v250
	v_mfma_f32_32x32x16_bf16 v[34:49], v[134:137], v[204:207], v[34:49]
	v_add_f32_e32 v250, v74, v250
	v_add_f32_e32 v250, v75, v250
	v_add_f32_e32 v250, v76, v250
	v_add_f32_e32 v250, v77, v250
	v_add_f32_e32 v250, v78, v250
	v_add_f32_e32 v250, v79, v250
	v_add_f32_e32 v250, v80, v250
	v_add_f32_e32 v250, v81, v250
	v_add_f32_e32 v196, v250, v196
	v_mfma_f32_32x32x16_bf16 v[50:65], v[138:141], v[208:211], v[50:65]
	s_cmp_gt_i32 s29, 1
	s_cbranch_scc1 .Lattn_p_mk1_bm0
	v_cmp_lt_i32_e64 s[42:43], 15, v253
	v_cmp_lt_i32_e64 s[44:45], 14, v253
	v_cmp_lt_i32_e64 s[46:47], 13, v253
	v_cmp_lt_i32_e64 s[48:49], 12, v253
	v_cndmask_b32_e64 v220, v194, v220, s[42:43]
	v_cndmask_b32_e64 v221, v194, v221, s[44:45]
	v_cndmask_b32_e64 v222, v194, v222, s[46:47]
	v_cndmask_b32_e64 v223, v194, v223, s[48:49]
	v_cmp_lt_i32_e64 s[42:43], 7, v253
	v_cmp_lt_i32_e64 s[44:45], 6, v253
	v_cmp_lt_i32_e64 s[46:47], 5, v253
	v_cmp_lt_i32_e64 s[48:49], 4, v253
	v_cndmask_b32_e64 v224, v194, v224, s[42:43]
	v_cndmask_b32_e64 v225, v194, v225, s[44:45]
	v_cndmask_b32_e64 v226, v194, v226, s[46:47]
	v_cndmask_b32_e64 v227, v194, v227, s[48:49]
	v_cmp_lt_i32_e64 s[42:43], -1, v253
	v_cmp_lt_i32_e64 s[44:45], -2, v253
	v_cmp_lt_i32_e64 s[46:47], -3, v253
	v_cmp_lt_i32_e64 s[48:49], -4, v253
	v_cndmask_b32_e64 v228, v194, v228, s[42:43]
	v_cndmask_b32_e64 v229, v194, v229, s[44:45]
	v_cndmask_b32_e64 v230, v194, v230, s[46:47]
	v_cndmask_b32_e64 v231, v194, v231, s[48:49]
	v_cmp_lt_i32_e64 s[42:43], -9, v253
	v_cmp_lt_i32_e64 s[44:45], -10, v253
	v_cmp_lt_i32_e64 s[46:47], -11, v253
	v_cmp_lt_i32_e64 s[48:49], -12, v253
	v_cndmask_b32_e64 v232, v194, v232, s[42:43]
	v_cndmask_b32_e64 v233, v194, v233, s[44:45]
	v_cndmask_b32_e64 v234, v194, v234, s[46:47]
	v_cndmask_b32_e64 v235, v194, v235, s[48:49]

; __device__ __forceinline__ unsigned cvt_pk_bf16(float lo, float hi) { unsigned r; asm("v_cvt_pk_bf16_f32 %0, %1, %2" : "=v"(r) : "v"(lo), "v"(hi)); return r; }
; __device__ __forceinline__ void attn_mfma(PP p, unsigned char* shm, int wv) {
;     ...
;                     float ls = 0.f;
; #pragma unroll
;                     for (int i = 0; i < 16; ++i) { s[i] = __builtin_amdgcn_exp2f(__builtin_fmaf(s[i], SC2, -mnew)); ls += s[i]; }
;                     lrun[qi] += ls;
;                     bf16x8 pf[2];
; #pragma unroll
;                     for (int s2 = 0; s2 < 2; ++s2) {
;                         u32x4 w; w.x = cvt_pk_bf16(s[8 * s2 + 0], s[8 * s2 + 1]); w.y = cvt_pk_bf16(s[8 * s2 + 2], s[8 * s2 + 3]);
;                         w.z = cvt_pk_bf16(s[8 * s2 + 4], s[8 * s2 + 5]); w.w = cvt_pk_bf16(s[8 * s2 + 6], s[8 * s2 + 7]);
;                         pf[s2] = __builtin_bit_cast(bf16x8, w);
;                     }
; #pragma unroll
;                     for (int db = 0; db < 2; ++db)
; #pragma unroll
;                         for (int s2 = 0; s2 < 2; ++s2) oacc[db][qi] = __builtin_amdgcn_mfma_f32_32x32x16_bf16(vf[db][s2], pf[s2], oacc[db][qi], 0, 0, 0);
;                 }
.Lattn_p_nr1_bm0:
	v_fma_f32 v236, v220, s31, -v249
	v_fma_f32 v237, v221, s31, -v249
	v_fma_f32 v238, v222, s31, -v249
	v_fma_f32 v239, v223, s31, -v249
	v_exp_f32_e32 v220, v236
	v_exp_f32_e32 v221, v237
	v_exp_f32_e32 v222, v238
	v_exp_f32_e32 v223, v239
	v_fma_f32 v236, v224, s31, -v249
	v_fma_f32 v237, v225, s31, -v249
	v_fma_f32 v238, v226, s31, -v249
	v_fma_f32 v239, v227, s31, -v249
	v_exp_f32_e32 v224, v236
	v_exp_f32_e32 v225, v237
	v_exp_f32_e32 v226, v238
	v_exp_f32_e32 v227, v239
	v_fma_f32 v236, v228, s31, -v249
	v_fma_f32 v237, v229, s31, -v249
	v_fma_f32 v238, v230, s31, -v249
	v_fma_f32 v239, v231, s31, -v249
	v_exp_f32_e32 v228, v236
	v_exp_f32_e32 v229, v237
	v_exp_f32_e32 v230, v238
	v_exp_f32_e32 v231, v239
	v_fma_f32 v236, v232, s31, -v249
	v_fma_f32 v237, v233, s31, -v249
	v_fma_f32 v238, v234, s31, -v249
	v_fma_f32 v239, v235, s31, -v249
	v_exp_f32_e32 v232, v236
	v_exp_f32_e32 v233, v237
	v_exp_f32_e32 v234, v238
	v_exp_f32_e32 v235, v239
	v_cvt_pk_bf16_f32 v212, v220, v221
	v_cvt_pk_bf16_f32 v213, v222, v223
	v_cvt_pk_bf16_f32 v214, v224, v225
	v_cvt_pk_bf16_f32 v215, v226, v227
	v_cvt_pk_bf16_f32 v216, v228, v229
	v_cvt_pk_bf16_f32 v217, v230, v231
	v_cvt_pk_bf16_f32 v218, v232, v233
	v_cvt_pk_bf16_f32 v219, v234, v235
	v_mfma_f32_32x32x16_bf16 v[18:33], v[142:145], v[212:215], v[18:33]
	v_add_f32_e32 v251, 0, v220
	v_add_f32_e32 v251, v221, v251
	v_add_f32_e32 v251, v222, v251
	v_add_f32_e32 v251, v223, v251
	v_add_f32_e32 v251, v224, v251
	v_mfma_f32_32x32x16_bf16 v[2:17], v[134:137], v[212:215], v[2:17]
	v_add_f32_e32 v251, v225, v251
	v_add_f32_e32 v251, v226, v251
	v_add_f32_e32 v251, v227, v251
	v_add_f32_e32 v251, v228, v251
	v_add_f32_e32 v251, v229, v251
	v_mfma_f32_32x32x16_bf16 v[18:33], v[138:141], v[216:219], v[18:33]
	v_add_f32_e32 v251, v230, v251
	v_add_f32_e32 v251, v231, v251
	v_add_f32_e32 v251, v232, v251
	v_add_f32_e32 v251, v233, v251
	v_mfma_f32_32x32x16_bf16 v[2:17], v[130:133], v[216:219], v[2:17]
	v_add_f32_e32 v251, v234, v251
	v_add_f32_e32 v251, v235, v251
	v_add_f32_e32 v1, v251, v1
	s_branch .LBB0_487

; __device__ __forceinline__ void attn_mfma(PP p, unsigned char* shm, int wv) {
;     ...
;                 bf16x8 kf[4];
; #pragma unroll
;                 for (int st = 0; st < 4; ++st) kf[st] = *(const bf16x8*)(Ks + (32 * kt + l31) * 72 + 16 * st + 8 * hl);
;                 bf16x8 vf[2][2];
; #pragma unroll
;                 for (int db = 0; db < 2; ++db)
; #pragma unroll
;                     for (int s2 = 0; s2 < 2; ++s2) {
;                         const bf16_t* vp = Vt + (32 * db + l31) * 132 + 32 * kt + 16 * s2 + 4 * hl;
;                         const u32x2 lo = *(const u32x2*)vp, hi = *(const u32x2*)(vp + 8);
;                         u32x4 w; w.x = lo.x; w.y = lo.y; w.z = hi.x; w.w = hi.y;
;                         vf[db][s2] = __builtin_bit_cast(bf16x8, w);
;                     }
; #pragma unroll
;                 for (int qi = 0; qi < 2; ++qi) {
;                     f32x16 s;
; #pragma unroll
;                     for (int i = 0; i < 16; ++i) s[i] = 0.f;
;                     __builtin_amdgcn_s_setprio(1);
; #pragma unroll
;                     for (int st = 0; st < 4; ++st) s = __builtin_amdgcn_mfma_f32_32x32x16_bf16(kf[st], qf[qi][st], s, 0, 0, 0);
;                     __builtin_amdgcn_s_setprio(0);
;                     if (ci == 0 || ci == 2) {
;                         asm volatile("");
;                         const int dl = (ci == 0) ? (32 * kt + 4 * hl - (64 * qh + 32 * qi + l31)) : ((64 * qh + 32 * qi + l31) - 32 * kt - 4 * hl);
; #pragma unroll
;                         for (int i = 0; i < 16; ++i) {
;                             const int ki = 8 * (i >> 2) + (i & 3);
;                             const bool ok = (ci == 0) ? (dl + ki >= 0) : (dl - ki >= 0);
;                             s[i] = ok ? s[i] : -1e30f;
;                         }
;                     }
.Lattn_p_loop_m2:
	v_add_u32_e32 v236, 0x2000, v199
	ds_read2_b64 v[142:145], v199 offset1:2
	ds_read2_b64 v[138:141], v199 offset0:4 offset1:6
	ds_read2_b64 v[134:137], v236 offset0:32 offset1:34
	ds_read2_b64 v[130:133], v236 offset0:36 offset1:38
	v_add_u32_e32 v199, 64, v199
	v_lshl_or_b32 v252, s40, 5, v181
	v_sub_u32_e32 v252, v180, v252
	v_add_u32_e32 v253, 32, v252
	s_sub_i32 s29, s40, s28
	v_mfma_f32_32x32x16_bf16 v[220:235], v[158:161], v[98:101], 0
	s_cmp_lt_i32 s29, 0
	s_cbranch_scc1 .Lattn_p_mk0_am2
	v_cmp_lt_i32_e64 s[42:43], -1, v252
	v_cmp_lt_i32_e64 s[44:45], 0, v252
	v_cmp_lt_i32_e64 s[46:47], 1, v252
	v_cmp_lt_i32_e64 s[48:49], 2, v252
	v_cndmask_b32_e64 v66, v194, v66, s[42:43]
	v_cndmask_b32_e64 v67, v194, v67, s[44:45]
	v_cndmask_b32_e64 v68, v194, v68, s[46:47]
	v_cndmask_b32_e64 v69, v194, v69, s[48:49]
	v_cmp_lt_i32_e64 s[42:43], 7, v252
	v_cmp_lt_i32_e64 s[44:45], 8, v252
	v_cmp_lt_i32_e64 s[46:47], 9, v252
	v_cmp_lt_i32_e64 s[48:49], 10, v252
	v_cndmask_b32_e64 v70, v194, v70, s[42:43]
	v_cndmask_b32_e64 v71, v194, v71, s[44:45]
	v_cndmask_b32_e64 v72, v194, v72, s[46:47]
	v_cndmask_b32_e64 v73, v194, v73, s[48:49]
	v_cmp_lt_i32_e64 s[42:43], 15, v252
	v_cmp_lt_i32_e64 s[44:45], 16, v252
	v_cmp_lt_i32_e64 s[46:47], 17, v252
	v_cmp_lt_i32_e64 s[48:49], 18, v252
	v_cndmask_b32_e64 v74, v194, v74, s[42:43]
	v_cndmask_b32_e64 v75, v194, v75, s[44:45]
	v_cndmask_b32_e64 v76, v194, v76, s[46:47]
	v_cndmask_b32_e64 v77, v194, v77, s[48:49]
	v_cmp_lt_i32_e64 s[42:43], 23, v252
	v_cmp_lt_i32_e64 s[44:45], 24, v252
	v_cmp_lt_i32_e64 s[46:47], 25, v252
	v_cmp_lt_i32_e64 s[48:49], 26, v252
	v_cndmask_b32_e64 v78, v194, v78, s[42:43]
	v_cndmask_b32_e64 v79, v194, v79, s[44:45]
	v_cndmask_b32_e64 v80, v194, v80, s[46:47]
	v_cndmask_b32_e64 v81, v194, v81, s[48:49]

; __device__ __forceinline__ void attn_mfma(PP p, unsigned char* shm, int wv) {
;     ...
;                     if (ci == 0 || ci == 2) {
;                         asm volatile("");
;                         const int dl = (ci == 0) ? (32 * kt + 4 * hl - (64 * qh + 32 * qi + l31)) : ((64 * qh + 32 * qi + l31) - 32 * kt - 4 * hl);
; #pragma unroll
;                         for (int i = 0; i < 16; ++i) {
;                             const int ki = 8 * (i >> 2) + (i & 3);
;                             const bool ok = (ci == 0) ? (dl + ki >= 0) : (dl - ki >= 0);
;                             s[i] = ok ? s[i] : -1e30f;
;                         }
;                     }
;                     float mx = s[0];
; #pragma unroll
;                     for (int i = 1; i < 16; ++i) mx = fmaxf(mx, s[i]);
;                     mx = fmaxf(mx, __shfl_xor(mx, 32));
;                     const float mnew = fmaxf(mrun[qi], mx * SC2);
;                     if (__builtin_amdgcn_ballot_w64(mnew > mrun[qi]) != 0ull) {
;                         const float alpha = __builtin_amdgcn_exp2f(mrun[qi] - mnew);
;                         lrun[qi] *= alpha;
; #pragma unroll
;                         for (int db = 0; db < 2; ++db)
; #pragma unroll
;                             for (int i = 0; i < 16; ++i) oacc[db][qi][i] *= alpha;
;                         mrun[qi] = mnew;
;                     }
;                     float ls = 0.f;
; #pragma unroll
;                     for (int i = 0; i < 16; ++i) { s[i] = __builtin_amdgcn_exp2f(__builtin_fmaf(s[i], SC2, -mnew)); ls += s[i]; }
;                     lrun[qi] += ls;
;                     bf16x8 pf[2];
; #pragma unroll
;                     for (int s2 = 0; s2 < 2; ++s2) {
;                         u32x4 w; w.x = cvt_pk_bf16(s[8 * s2 + 0], s[8 * s2 + 1]); w.y = cvt_pk_bf16(s[8 * s2 + 2], s[8 * s2 + 3]);
;                         w.z = cvt_pk_bf16(s[8 * s2 + 4], s[8 * s2 + 5]); w.w = cvt_pk_bf16(s[8 * s2 + 6], s[8 * s2 + 7]);
;                         pf[s2] = __builtin_bit_cast(bf16x8, w);
;                     }
; #pragma unroll
;                     for (int db = 0; db < 2; ++db)
; #pragma unroll
;                         for (int s2 = 0; s2 < 2; ++s2) oacc[db][qi] = __builtin_amdgcn_mfma_f32_32x32x16_bf16(vf[db][s2], pf[s2], oacc[db][qi], 0, 0, 0);
;                 }
.Lattn_p_nr0_am2:
	v_fma_f32 v236, v66, s31, -v248
	v_fma_f32 v237, v67, s31, -v248
	v_fma_f32 v238, v68, s31, -v248
	v_fma_f32 v239, v69, s31, -v248
	v_exp_f32_e32 v66, v236
	v_exp_f32_e32 v67, v237
	v_exp_f32_e32 v68, v238
	v_exp_f32_e32 v69, v239
	v_mfma_f32_32x32x16_bf16 v[220:235], v[150:153], v[106:109], v[220:235]
	v_fma_f32 v236, v70, s31, -v248
	v_fma_f32 v237, v71, s31, -v248
	v_fma_f32 v238, v72, s31, -v248
	v_fma_f32 v239, v73, s31, -v248
	v_exp_f32_e32 v70, v236
	v_exp_f32_e32 v71, v237
	v_exp_f32_e32 v72, v238
	v_exp_f32_e32 v73, v239
	v_fma_f32 v236, v74, s31, -v248
	v_fma_f32 v237, v75, s31, -v248
	v_fma_f32 v238, v76, s31, -v248
	v_fma_f32 v239, v77, s31, -v248
	v_exp_f32_e32 v74, v236
	v_exp_f32_e32 v75, v237
	v_exp_f32_e32 v76, v238
	v_exp_f32_e32 v77, v239
	v_mfma_f32_32x32x16_bf16 v[220:235], v[146:149], v[110:113], v[220:235]
	ds_read_b128 v[158:161], v200
	ds_read_b128 v[154:157], v200 offset:32
	ds_read_b128 v[150:153], v200 offset:64
	ds_read_b128 v[146:149], v200 offset:96
	v_add_u32_e32 v200, 0x1200, v200
	v_fma_f32 v236, v78, s31, -v248
	v_fma_f32 v237, v79, s31, -v248
	v_fma_f32 v238, v80, s31, -v248
	v_fma_f32 v239, v81, s31, -v248
	v_exp_f32_e32 v78, v236
	v_exp_f32_e32 v79, v237
	v_exp_f32_e32 v80, v238
	v_exp_f32_e32 v81, v239
	v_cvt_pk_bf16_f32 v204, v66, v67
	v_cvt_pk_bf16_f32 v205, v68, v69
	v_cvt_pk_bf16_f32 v206, v70, v71
	v_cvt_pk_bf16_f32 v207, v72, v73
	v_cvt_pk_bf16_f32 v208, v74, v75
	v_cvt_pk_bf16_f32 v209, v76, v77
	v_cvt_pk_bf16_f32 v210, v78, v79
	v_cvt_pk_bf16_f32 v211, v80, v81
	s_waitcnt lgkmcnt(4)
	v_mfma_f32_32x32x16_bf16 v[50:65], v[142:145], v[204:207], v[50:65]
	v_add_f32_e32 v250, 0, v66
	v_add_f32_e32 v250, v67, v250
	v_add_f32_e32 v250, v68, v250
	v_add_f32_e32 v250, v69, v250
	v_add_f32_e32 v250, v70, v250
	v_add_f32_e32 v250, v71, v250
	v_add_f32_e32 v250, v72, v250
	v_add_f32_e32 v250, v73, v250
	v_mfma_f32_32x32x16_bf16 v[34:49], v[134:137], v[204:207], v[34:49]
	v_add_f32_e32 v250, v74, v250
	v_add_f32_e32 v250, v75, v250
	v_add_f32_e32 v250, v76, v250
	v_add_f32_e32 v250, v77, v250
	v_add_f32_e32 v250, v78, v250
	v_add_f32_e32 v250, v79, v250
	v_add_f32_e32 v250, v80, v250
	v_add_f32_e32 v250, v81, v250
	v_add_f32_e32 v196, v250, v196
	v_mfma_f32_32x32x16_bf16 v[50:65], v[138:141], v[208:211], v[50:65]
	s_cmp_lt_i32 s29, 1
	s_cbranch_scc1 .Lattn_p_mk1_am2
	v_cmp_lt_i32_e64 s[42:43], -1, v253
	v_cmp_lt_i32_e64 s[44:45], 0, v253
	v_cmp_lt_i32_e64 s[46:47], 1, v253
	v_cmp_lt_i32_e64 s[48:49], 2, v253
	v_cndmask_b32_e64 v220, v194, v220, s[42:43]
	v_cndmask_b32_e64 v221, v194, v221, s[44:45]
	v_cndmask_b32_e64 v222, v194, v222, s[46:47]
	v_cndmask_b32_e64 v223, v194, v223, s[48:49]
	v_cmp_lt_i32_e64 s[42:43], 7, v253
	v_cmp_lt_i32_e64 s[44:45], 8, v253
	v_cmp_lt_i32_e64 s[46:47], 9, v253
	v_cmp_lt_i32_e64 s[48:49], 10, v253
	v_cndmask_b32_e64 v224, v194, v224, s[42:43]
	v_cndmask_b32_e64 v225, v194, v225, s[44:45]
	v_cndmask_b32_e64 v226, v194, v226, s[46:47]
	v_cndmask_b32_e64 v227, v194, v227, s[48:49]
	v_cmp_lt_i32_e64 s[42:43], 15, v253
	v_cmp_lt_i32_e64 s[44:45], 16, v253
	v_cmp_lt_i32_e64 s[46:47], 17, v253
	v_cmp_lt_i32_e64 s[48:49], 18, v253
	v_cndmask_b32_e64 v228, v194, v228, s[42:43]
	v_cndmask_b32_e64 v229, v194, v229, s[44:45]
	v_cndmask_b32_e64 v230, v194, v230, s[46:47]
	v_cndmask_b32_e64 v231, v194, v231, s[48:49]
	v_cmp_lt_i32_e64 s[42:43], 23, v253
	v_cmp_lt_i32_e64 s[44:45], 24, v253
	v_cmp_lt_i32_e64 s[46:47], 25, v253
	v_cmp_lt_i32_e64 s[48:49], 26, v253
	v_cndmask_b32_e64 v232, v194, v232, s[42:43]
	v_cndmask_b32_e64 v233, v194, v233, s[44:45]
	v_cndmask_b32_e64 v234, v194, v234, s[46:47]
	v_cndmask_b32_e64 v235, v194, v235, s[48:49]

; __device__ __forceinline__ void attn_mfma(PP p, unsigned char* shm, int wv) {
;     ...
;                     if (ci == 0 || ci == 2) {
;                         asm volatile("");
;                         const int dl = (ci == 0) ? (32 * kt + 4 * hl - (64 * qh + 32 * qi + l31)) : ((64 * qh + 32 * qi + l31) - 32 * kt - 4 * hl);
; #pragma unroll
;                         for (int i = 0; i < 16; ++i) {
;                             const int ki = 8 * (i >> 2) + (i & 3);
;                             const bool ok = (ci == 0) ? (dl + ki >= 0) : (dl - ki >= 0);
;                             s[i] = ok ? s[i] : -1e30f;
;                         }
;                     }
;                     float mx = s[0];
; #pragma unroll
;                     for (int i = 1; i < 16; ++i) mx = fmaxf(mx, s[i]);
;                     mx = fmaxf(mx, __shfl_xor(mx, 32));
;                     const float mnew = fmaxf(mrun[qi], mx * SC2);
;                     if (__builtin_amdgcn_ballot_w64(mnew > mrun[qi]) != 0ull) {
;                         const float alpha = __builtin_amdgcn_exp2f(mrun[qi] - mnew);
;                         lrun[qi] *= alpha;
; #pragma unroll
;                         for (int db = 0; db < 2; ++db)
; #pragma unroll
;                             for (int i = 0; i < 16; ++i) oacc[db][qi][i] *= alpha;
;                         mrun[qi] = mnew;
;                     }
;                     float ls = 0.f;
; #pragma unroll
;                     for (int i = 0; i < 16; ++i) { s[i] = __builtin_amdgcn_exp2f(__builtin_fmaf(s[i], SC2, -mnew)); ls += s[i]; }
;                     lrun[qi] += ls;
;                     bf16x8 pf[2];
; #pragma unroll
;                     for (int s2 = 0; s2 < 2; ++s2) {
;                         u32x4 w; w.x = cvt_pk_bf16(s[8 * s2 + 0], s[8 * s2 + 1]); w.y = cvt_pk_bf16(s[8 * s2 + 2], s[8 * s2 + 3]);
;                         w.z = cvt_pk_bf16(s[8 * s2 + 4], s[8 * s2 + 5]); w.w = cvt_pk_bf16(s[8 * s2 + 6], s[8 * s2 + 7]);
;                         pf[s2] = __builtin_bit_cast(bf16x8, w);
;                     }
; #pragma unroll
;                     for (int db = 0; db < 2; ++db)
; #pragma unroll
;                         for (int s2 = 0; s2 < 2; ++s2) oacc[db][qi] = __builtin_amdgcn_mfma_f32_32x32x16_bf16(vf[db][s2], pf[s2], oacc[db][qi], 0, 0, 0);
.Lattn_p_nr0_bm2:
	v_fma_f32 v236, v66, s31, -v248
	v_fma_f32 v237, v67, s31, -v248
	v_fma_f32 v238, v68, s31, -v248
	v_fma_f32 v239, v69, s31, -v248
	v_exp_f32_e32 v66, v236
	v_exp_f32_e32 v67, v237
	v_exp_f32_e32 v68, v238
	v_exp_f32_e32 v69, v239
	v_mfma_f32_32x32x16_bf16 v[220:235], v[150:153], v[106:109], v[220:235]
	v_fma_f32 v236, v70, s31, -v248
	v_fma_f32 v237, v71, s31, -v248
	v_fma_f32 v238, v72, s31, -v248
	v_fma_f32 v239, v73, s31, -v248
	v_exp_f32_e32 v70, v236
	v_exp_f32_e32 v71, v237
	v_exp_f32_e32 v72, v238
	v_exp_f32_e32 v73, v239
	v_fma_f32 v236, v74, s31, -v248
	v_fma_f32 v237, v75, s31, -v248
	v_fma_f32 v238, v76, s31, -v248
	v_fma_f32 v239, v77, s31, -v248
	v_exp_f32_e32 v74, v236
	v_exp_f32_e32 v75, v237
	v_exp_f32_e32 v76, v238
	v_exp_f32_e32 v77, v239
	v_mfma_f32_32x32x16_bf16 v[220:235], v[146:149], v[110:113], v[220:235]
	v_fma_f32 v236, v78, s31, -v248
	v_fma_f32 v237, v79, s31, -v248
	v_fma_f32 v238, v80, s31, -v248
	v_fma_f32 v239, v81, s31, -v248
	v_exp_f32_e32 v78, v236
	v_exp_f32_e32 v79, v237
	v_exp_f32_e32 v80, v238
	v_exp_f32_e32 v81, v239
	v_cvt_pk_bf16_f32 v204, v66, v67
	v_cvt_pk_bf16_f32 v205, v68, v69
	v_cvt_pk_bf16_f32 v206, v70, v71
	v_cvt_pk_bf16_f32 v207, v72, v73
	v_cvt_pk_bf16_f32 v208, v74, v75
	v_cvt_pk_bf16_f32 v209, v76, v77
	v_cvt_pk_bf16_f32 v210, v78, v79
	v_cvt_pk_bf16_f32 v211, v80, v81
	s_waitcnt lgkmcnt(0)
	v_mfma_f32_32x32x16_bf16 v[50:65], v[142:145], v[204:207], v[50:65]
	v_add_f32_e32 v250, 0, v66
	v_add_f32_e32 v250, v67, v250
	v_add_f32_e32 v250, v68, v250
	v_add_f32_e32 v250, v69, v250
	v_add_f32_e32 v250, v70, v250
	v_add_f32_e32 v250, v71, v250
	v_add_f32_e32 v250, v72, v250
	v_add_f32_e32 v250, v73, v250
	v_mfma_f32_32x32x16_bf16 v[34:49], v[134:137], v[204:207], v[34:49]
	v_add_f32_e32 v250, v74, v250
	v_add_f32_e32 v250, v75, v250
	v_add_f32_e32 v250, v76, v250
	v_add_f32_e32 v250, v77, v250
	v_add_f32_e32 v250, v78, v250
	v_add_f32_e32 v250, v79, v250
	v_add_f32_e32 v250, v80, v250
	v_add_f32_e32 v250, v81, v250
	v_add_f32_e32 v196, v250, v196
	v_mfma_f32_32x32x16_bf16 v[50:65], v[138:141], v[208:211], v[50:65]
	s_cmp_lt_i32 s29, 1
	s_cbranch_scc1 .Lattn_p_mk1_bm2
	v_cmp_lt_i32_e64 s[42:43], -1, v253
	v_cmp_lt_i32_e64 s[44:45], 0, v253
	v_cmp_lt_i32_e64 s[46:47], 1, v253
	v_cmp_lt_i32_e64 s[48:49], 2, v253
	v_cndmask_b32_e64 v220, v194, v220, s[42:43]
	v_cndmask_b32_e64 v221, v194, v221, s[44:45]
	v_cndmask_b32_e64 v222, v194, v222, s[46:47]
	v_cndmask_b32_e64 v223, v194, v223, s[48:49]
	v_cmp_lt_i32_e64 s[42:43], 7, v253
	v_cmp_lt_i32_e64 s[44:45], 8, v253
	v_cmp_lt_i32_e64 s[46:47], 9, v253
	v_cmp_lt_i32_e64 s[48:49], 10, v253
	v_cndmask_b32_e64 v224, v194, v224, s[42:43]
	v_cndmask_b32_e64 v225, v194, v225, s[44:45]
	v_cndmask_b32_e64 v226, v194, v226, s[46:47]
	v_cndmask_b32_e64 v227, v194, v227, s[48:49]
	v_cmp_lt_i32_e64 s[42:43], 15, v253
	v_cmp_lt_i32_e64 s[44:45], 16, v253
	v_cmp_lt_i32_e64 s[46:47], 17, v253
	v_cmp_lt_i32_e64 s[48:49], 18, v253
	v_cndmask_b32_e64 v228, v194, v228, s[42:43]
	v_cndmask_b32_e64 v229, v194, v229, s[44:45]
	v_cndmask_b32_e64 v230, v194, v230, s[46:47]
	v_cndmask_b32_e64 v231, v194, v231, s[48:49]
	v_cmp_lt_i32_e64 s[42:43], 23, v253
	v_cmp_lt_i32_e64 s[44:45], 24, v253
	v_cmp_lt_i32_e64 s[46:47], 25, v253
	v_cmp_lt_i32_e64 s[48:49], 26, v253
	v_cndmask_b32_e64 v232, v194, v232, s[42:43]
	v_cndmask_b32_e64 v233, v194, v233, s[44:45]
	v_cndmask_b32_e64 v234, v194, v234, s[46:47]
	v_cndmask_b32_e64 v235, v194, v235, s[48:49]
